# same as next version but without the DN step-B LDS hoist (A/B reference)
# speedup vs baseline: 1.0077x; 1.0077x over previous
.LBB0_913:
	s_add_i32 s22, s52, 0xfffff000
	s_lshr_b32 s23, s22, 10
	s_mulk_i32 s23, 0x3000
	s_cmp_lt_u32 s52, 0x1000
	s_cselect_b32 s22, s52, s22
	s_cselect_b32 s23, 0xc000, s23
	s_cselect_b32 s18, s68, s70
	s_cselect_b32 s19, s69, s71
	s_lshl_b32 s22, s22, 13
	s_add_u32 s98, s18, s22
	s_addc_u32 s99, s19, 0
	s_lshl_b32 s22, s52, 12
	s_add_u32 s100, s6, s22
	s_addc_u32 s101, s7, 0
	s_lshl_b32 s23, s23, 2
	s_add_u32 s22, s28, s23
	s_addc_u32 s23, s29, 0
	s_add_u32 s22, s22, 0x163c4000
	s_addc_u32 s23, s23, 0
	v_lshlrev_b32_e32 v246, 3, v224
	v_lshlrev_b32_e32 v247, 2, v224
	v_and_b32_e32 v246, 0xe0, v246
	v_and_b32_e32 v247, 12, v247
	v_or_b32_e32 v246, v246, v247
	v_lshrrev_b32_e32 v247, 5, v224
	v_or_b32_e32 v248, s50, v246
	v_lshlrev_b32_e32 v245, 2, v248
	v_lshl_add_u32 v242, v247, 13, v245
	v_lshlrev_b32_e32 v248, 1, v248
	v_lshl_add_u32 v243, v247, 12, v248
	v_mul_u32_u24_e32 v247, 0x410, v247
	v_lshl_add_u32 v244, v246, 2, v247
	v_add_u32_e32 v244, 16, v244
	global_load_dwordx4 v[234:237], v245, s[22:23]
	global_load_dwordx4 v[238:241], v245, s[22:23] offset:64
	global_load_dwordx4 v[168:171], v242, s[98:99]
	global_load_dwordx4 v[172:175], v242, s[98:99] offset:64
	s_add_u32 s18, s98, 0x20000
	s_addc_u32 s19, s99, 0
	global_load_dwordx4 v[176:179], v242, s[18:19]
	global_load_dwordx4 v[180:183], v242, s[18:19] offset:64
	s_add_u32 s18, s98, 0x80000
	s_addc_u32 s19, s99, 0
	global_load_dwordx4 v[184:187], v242, s[18:19]
	global_load_dwordx4 v[188:191], v242, s[18:19] offset:64
	s_add_u32 s18, s98, 0xa0000
	s_addc_u32 s19, s99, 0
	global_load_dwordx4 v[192:195], v242, s[18:19]
	global_load_dwordx4 v[196:199], v242, s[18:19] offset:64
	ds_write2_b32 v146, v104, v108 offset1:16
	v_add_u32_e32 v104, 0x400, v146
	ds_write2_b32 v104, v105, v109 offset0:4 offset1:20
	v_add_u32_e32 v105, 0x800, v146
	ds_write2_b32 v105, v106, v110 offset0:8 offset1:24
	v_add_u32_e32 v106, 0xc00, v146
	ds_write2_b32 v106, v107, v111 offset0:12 offset1:28
	ds_write2_b32 v146, v120, v124 offset0:128 offset1:144
	ds_write2_b32 v104, v121, v125 offset0:132 offset1:148
	ds_write2_b32 v105, v122, v126 offset0:136 offset1:152
	ds_write2_b32 v106, v123, v127 offset0:140 offset1:156
	v_add_u32_e32 v107, 0x4000, v146
	ds_write2_b32 v107, v96, v100 offset0:64 offset1:80
	v_add_u32_e32 v108, 0x4400, v146
	v_add_u32_e32 v109, 0x4800, v146
	v_add_u32_e32 v110, 0x4c00, v146
	v_mov_b32_e32 v96, v224
	ds_write2_b32 v108, v97, v101 offset0:68 offset1:84
	ds_write2_b32 v109, v98, v102 offset0:72 offset1:88
	ds_write2_b32 v110, v99, v103 offset0:76 offset1:92
	ds_write2_b32 v107, v112, v116 offset0:192 offset1:208
	ds_write2_b32 v108, v113, v117 offset0:196 offset1:212
	ds_write2_b32 v109, v114, v118 offset0:200 offset1:216
	ds_write2_b32 v110, v115, v119 offset0:204 offset1:220
	s_waitcnt lgkmcnt(0)
	s_barrier
	ds_read_b128 v[200:203], v244 offset:0
	ds_read_b128 v[204:207], v244 offset:64
	ds_read_b128 v[208:211], v244 offset:16640
	ds_read_b128 v[212:215], v244 offset:16704
	ds_read_b128 v[216:219], v244 offset:33280
	ds_read_b128 v[220:223], v244 offset:33344
	ds_read_b128 v[226:229], v244 offset:49920
	ds_read_b128 v[230:233], v244 offset:49984
	s_waitcnt vmcnt(0)
	s_waitcnt lgkmcnt(6)
	v_pk_fma_f32 v[170:171], v[236:237], v[202:203], v[170:171]
	v_pk_fma_f32 v[168:169], v[234:235], v[200:201], v[168:169]
	v_pk_fma_f32 v[174:175], v[240:241], v[206:207], v[174:175]
	v_pk_fma_f32 v[172:173], v[238:239], v[204:205], v[172:173]
	v_cvt_pk_bf16_f32 v171, v170, v171
	v_cvt_pk_bf16_f32 v170, v168, v169
	v_cvt_pk_bf16_f32 v175, v174, v175
	v_cvt_pk_bf16_f32 v174, v172, v173
	global_store_dwordx2 v243, v[170:171], s[100:101]
	global_store_dwordx2 v243, v[174:175], s[100:101] offset:32
	s_waitcnt lgkmcnt(4)
	v_pk_fma_f32 v[178:179], v[236:237], v[210:211], v[178:179]
	v_pk_fma_f32 v[176:177], v[234:235], v[208:209], v[176:177]
	v_pk_fma_f32 v[182:183], v[240:241], v[214:215], v[182:183]
	v_pk_fma_f32 v[180:181], v[238:239], v[212:213], v[180:181]
	v_cvt_pk_bf16_f32 v179, v178, v179
	v_cvt_pk_bf16_f32 v178, v176, v177
	v_cvt_pk_bf16_f32 v183, v182, v183
	v_cvt_pk_bf16_f32 v182, v180, v181
	s_add_u32 s18, s100, 0x10000
	s_addc_u32 s19, s101, 0
	global_store_dwordx2 v243, v[178:179], s[18:19]
	global_store_dwordx2 v243, v[182:183], s[18:19] offset:32
	s_waitcnt lgkmcnt(2)
	v_pk_fma_f32 v[186:187], v[236:237], v[218:219], v[186:187]
	v_pk_fma_f32 v[184:185], v[234:235], v[216:217], v[184:185]
	v_pk_fma_f32 v[190:191], v[240:241], v[222:223], v[190:191]
	v_pk_fma_f32 v[188:189], v[238:239], v[220:221], v[188:189]
	v_cvt_pk_bf16_f32 v187, v186, v187
	v_cvt_pk_bf16_f32 v186, v184, v185
	v_cvt_pk_bf16_f32 v191, v190, v191
	v_cvt_pk_bf16_f32 v190, v188, v189
	s_add_u32 s18, s100, 0x40000
	s_addc_u32 s19, s101, 0
	global_store_dwordx2 v243, v[186:187], s[18:19]
	global_store_dwordx2 v243, v[190:191], s[18:19] offset:32
	s_waitcnt lgkmcnt(0)
	v_pk_fma_f32 v[194:195], v[236:237], v[228:229], v[194:195]
	v_pk_fma_f32 v[192:193], v[234:235], v[226:227], v[192:193]
	v_pk_fma_f32 v[198:199], v[240:241], v[232:233], v[198:199]
	v_pk_fma_f32 v[196:197], v[238:239], v[230:231], v[196:197]
	v_cvt_pk_bf16_f32 v195, v194, v195
	v_cvt_pk_bf16_f32 v194, v192, v193
	v_cvt_pk_bf16_f32 v199, v198, v199
	v_cvt_pk_bf16_f32 v198, v196, v197
	s_add_u32 s18, s100, 0x50000
	s_addc_u32 s19, s101, 0
	global_store_dwordx2 v243, v[194:195], s[18:19]
	global_store_dwordx2 v243, v[198:199], s[18:19] offset:32
	s_add_u32 s18, s98, 0x40000
	s_addc_u32 s19, s99, 0
	global_load_dwordx4 v[168:171], v242, s[18:19]
	global_load_dwordx4 v[172:175], v242, s[18:19] offset:64
	s_add_u32 s18, s98, 0x60000
	s_addc_u32 s19, s99, 0
	global_load_dwordx4 v[176:179], v242, s[18:19]
	global_load_dwordx4 v[180:183], v242, s[18:19] offset:64
	s_add_u32 s18, s98, 0xc0000
	s_addc_u32 s19, s99, 0
	global_load_dwordx4 v[184:187], v242, s[18:19]
	global_load_dwordx4 v[188:191], v242, s[18:19] offset:64
	s_add_u32 s18, s98, 0xe0000
	s_addc_u32 s19, s99, 0
	global_load_dwordx4 v[192:195], v242, s[18:19]
	global_load_dwordx4 v[196:199], v242, s[18:19] offset:64
	s_barrier
	ds_write2_b32 v146, v72, v76 offset1:16
	ds_write2_b32 v104, v73, v77 offset0:4 offset1:20
	ds_write2_b32 v105, v74, v78 offset0:8 offset1:24
	ds_write2_b32 v106, v75, v79 offset0:12 offset1:28
	ds_write2_b32 v146, v88, v92 offset0:128 offset1:144
	ds_write2_b32 v104, v89, v93 offset0:132 offset1:148
	ds_write2_b32 v105, v90, v94 offset0:136 offset1:152
	ds_write2_b32 v106, v91, v95 offset0:140 offset1:156
	ds_write2_b32 v107, v64, v68 offset0:64 offset1:80
	ds_write2_b32 v108, v65, v69 offset0:68 offset1:84
	ds_write2_b32 v109, v66, v70 offset0:72 offset1:88
	ds_write2_b32 v110, v67, v71 offset0:76 offset1:92
	ds_write2_b32 v107, v80, v84 offset0:192 offset1:208
	ds_write2_b32 v108, v81, v85 offset0:196 offset1:212
	ds_write2_b32 v109, v82, v86 offset0:200 offset1:216
	ds_write2_b32 v110, v83, v87 offset0:204 offset1:220
	s_waitcnt lgkmcnt(0)
	s_barrier
	ds_read_b128 v[200:203], v244 offset:0
	ds_read_b128 v[204:207], v244 offset:64
	ds_read_b128 v[208:211], v244 offset:16640
	ds_read_b128 v[212:215], v244 offset:16704
	ds_read_b128 v[216:219], v244 offset:33280
	ds_read_b128 v[220:223], v244 offset:33344
	ds_read_b128 v[226:229], v244 offset:49920
	ds_read_b128 v[230:233], v244 offset:49984
	s_waitcnt vmcnt(0)
	s_waitcnt lgkmcnt(6)
	v_pk_fma_f32 v[170:171], v[236:237], v[202:203], v[170:171]
	v_pk_fma_f32 v[168:169], v[234:235], v[200:201], v[168:169]
	v_pk_fma_f32 v[174:175], v[240:241], v[206:207], v[174:175]
	v_pk_fma_f32 v[172:173], v[238:239], v[204:205], v[172:173]
	v_cvt_pk_bf16_f32 v171, v170, v171
	v_cvt_pk_bf16_f32 v170, v168, v169
	v_cvt_pk_bf16_f32 v175, v174, v175
	v_cvt_pk_bf16_f32 v174, v172, v173
	s_add_u32 s18, s100, 0x20000
	s_addc_u32 s19, s101, 0
	global_store_dwordx2 v243, v[170:171], s[18:19]
	global_store_dwordx2 v243, v[174:175], s[18:19] offset:32
	s_waitcnt lgkmcnt(4)
	v_pk_fma_f32 v[178:179], v[236:237], v[210:211], v[178:179]
	v_pk_fma_f32 v[176:177], v[234:235], v[208:209], v[176:177]
	v_pk_fma_f32 v[182:183], v[240:241], v[214:215], v[182:183]
	v_pk_fma_f32 v[180:181], v[238:239], v[212:213], v[180:181]
	v_cvt_pk_bf16_f32 v179, v178, v179
	v_cvt_pk_bf16_f32 v178, v176, v177
	v_cvt_pk_bf16_f32 v183, v182, v183
	v_cvt_pk_bf16_f32 v182, v180, v181
	s_add_u32 s18, s100, 0x30000
	s_addc_u32 s19, s101, 0
	global_store_dwordx2 v243, v[178:179], s[18:19]
	global_store_dwordx2 v243, v[182:183], s[18:19] offset:32
	s_waitcnt lgkmcnt(2)
	v_pk_fma_f32 v[186:187], v[236:237], v[218:219], v[186:187]
	v_pk_fma_f32 v[184:185], v[234:235], v[216:217], v[184:185]
	v_pk_fma_f32 v[190:191], v[240:241], v[222:223], v[190:191]
	v_pk_fma_f32 v[188:189], v[238:239], v[220:221], v[188:189]
	v_cvt_pk_bf16_f32 v187, v186, v187
	v_cvt_pk_bf16_f32 v186, v184, v185
	v_cvt_pk_bf16_f32 v191, v190, v191
	v_cvt_pk_bf16_f32 v190, v188, v189
	s_add_u32 s18, s100, 0x60000
	s_addc_u32 s19, s101, 0
	global_store_dwordx2 v243, v[186:187], s[18:19]
	global_store_dwordx2 v243, v[190:191], s[18:19] offset:32
	s_waitcnt lgkmcnt(0)
	v_pk_fma_f32 v[194:195], v[236:237], v[228:229], v[194:195]
	v_pk_fma_f32 v[192:193], v[234:235], v[226:227], v[192:193]
	v_pk_fma_f32 v[198:199], v[240:241], v[232:233], v[198:199]
	v_pk_fma_f32 v[196:197], v[238:239], v[230:231], v[196:197]
	v_cvt_pk_bf16_f32 v195, v194, v195
	v_cvt_pk_bf16_f32 v194, v192, v193
	v_cvt_pk_bf16_f32 v199, v198, v199
	v_cvt_pk_bf16_f32 v198, v196, v197
	s_add_u32 s18, s100, 0x70000
	s_addc_u32 s19, s101, 0
	global_store_dwordx2 v243, v[194:195], s[18:19]
	global_store_dwordx2 v243, v[198:199], s[18:19] offset:32
	s_add_u32 s18, s98, 0x100000
	s_addc_u32 s19, s99, 0
	global_load_dwordx4 v[168:171], v242, s[18:19]
	global_load_dwordx4 v[172:175], v242, s[18:19] offset:64
	s_add_u32 s18, s98, 0x120000
	s_addc_u32 s19, s99, 0
	global_load_dwordx4 v[176:179], v242, s[18:19]
	global_load_dwordx4 v[180:183], v242, s[18:19] offset:64
	s_add_u32 s18, s98, 0x180000
	s_addc_u32 s19, s99, 0
	global_load_dwordx4 v[184:187], v242, s[18:19]
	global_load_dwordx4 v[188:191], v242, s[18:19] offset:64
	s_add_u32 s18, s98, 0x1a0000
	s_addc_u32 s19, s99, 0
	global_load_dwordx4 v[192:195], v242, s[18:19]
	global_load_dwordx4 v[196:199], v242, s[18:19] offset:64
	s_barrier
	ds_write2_b32 v146, v40, v44 offset1:16
	ds_write2_b32 v104, v41, v45 offset0:4 offset1:20
	ds_write2_b32 v105, v42, v46 offset0:8 offset1:24
	ds_write2_b32 v106, v43, v47 offset0:12 offset1:28
	ds_write2_b32 v146, v56, v60 offset0:128 offset1:144
	ds_write2_b32 v104, v57, v61 offset0:132 offset1:148
	ds_write2_b32 v105, v58, v62 offset0:136 offset1:152
	ds_write2_b32 v106, v59, v63 offset0:140 offset1:156
	ds_write2_b32 v107, v32, v36 offset0:64 offset1:80
	ds_write2_b32 v108, v33, v37 offset0:68 offset1:84
	ds_write2_b32 v109, v34, v38 offset0:72 offset1:88
	ds_write2_b32 v110, v35, v39 offset0:76 offset1:92
	ds_write2_b32 v107, v48, v52 offset0:192 offset1:208
	ds_write2_b32 v108, v49, v53 offset0:196 offset1:212
	ds_write2_b32 v109, v50, v54 offset0:200 offset1:216
	ds_write2_b32 v110, v51, v55 offset0:204 offset1:220
	s_waitcnt lgkmcnt(0)
	s_barrier
	ds_read_b128 v[200:203], v244 offset:0
	ds_read_b128 v[204:207], v244 offset:64
	ds_read_b128 v[208:211], v244 offset:16640
	ds_read_b128 v[212:215], v244 offset:16704
	ds_read_b128 v[216:219], v244 offset:33280
	ds_read_b128 v[220:223], v244 offset:33344
	ds_read_b128 v[226:229], v244 offset:49920
	ds_read_b128 v[230:233], v244 offset:49984
	s_waitcnt vmcnt(0)
	s_waitcnt lgkmcnt(6)
	v_pk_fma_f32 v[170:171], v[236:237], v[202:203], v[170:171]
	v_pk_fma_f32 v[168:169], v[234:235], v[200:201], v[168:169]
	v_pk_fma_f32 v[174:175], v[240:241], v[206:207], v[174:175]
	v_pk_fma_f32 v[172:173], v[238:239], v[204:205], v[172:173]
	v_cvt_pk_bf16_f32 v171, v170, v171
	v_cvt_pk_bf16_f32 v170, v168, v169
	v_cvt_pk_bf16_f32 v175, v174, v175
	v_cvt_pk_bf16_f32 v174, v172, v173
	s_add_u32 s18, s100, 0x80000
	s_addc_u32 s19, s101, 0
	global_store_dwordx2 v243, v[170:171], s[18:19]
	global_store_dwordx2 v243, v[174:175], s[18:19] offset:32
	s_waitcnt lgkmcnt(4)
	v_pk_fma_f32 v[178:179], v[236:237], v[210:211], v[178:179]
	v_pk_fma_f32 v[176:177], v[234:235], v[208:209], v[176:177]
	v_pk_fma_f32 v[182:183], v[240:241], v[214:215], v[182:183]
	v_pk_fma_f32 v[180:181], v[238:239], v[212:213], v[180:181]
	v_cvt_pk_bf16_f32 v179, v178, v179
	v_cvt_pk_bf16_f32 v178, v176, v177
	v_cvt_pk_bf16_f32 v183, v182, v183
	v_cvt_pk_bf16_f32 v182, v180, v181
	s_add_u32 s18, s100, 0x90000
	s_addc_u32 s19, s101, 0
	global_store_dwordx2 v243, v[178:179], s[18:19]
	global_store_dwordx2 v243, v[182:183], s[18:19] offset:32
	s_waitcnt lgkmcnt(2)
	v_pk_fma_f32 v[186:187], v[236:237], v[218:219], v[186:187]
	v_pk_fma_f32 v[184:185], v[234:235], v[216:217], v[184:185]
	v_pk_fma_f32 v[190:191], v[240:241], v[222:223], v[190:191]
	v_pk_fma_f32 v[188:189], v[238:239], v[220:221], v[188:189]
	v_cvt_pk_bf16_f32 v187, v186, v187
	v_cvt_pk_bf16_f32 v186, v184, v185
	v_cvt_pk_bf16_f32 v191, v190, v191
	v_cvt_pk_bf16_f32 v190, v188, v189
	s_add_u32 s18, s100, 0xc0000
	s_addc_u32 s19, s101, 0
	global_store_dwordx2 v243, v[186:187], s[18:19]
	global_store_dwordx2 v243, v[190:191], s[18:19] offset:32
	s_waitcnt lgkmcnt(0)
	v_pk_fma_f32 v[194:195], v[236:237], v[228:229], v[194:195]
	v_pk_fma_f32 v[192:193], v[234:235], v[226:227], v[192:193]
	v_pk_fma_f32 v[198:199], v[240:241], v[232:233], v[198:199]
	v_pk_fma_f32 v[196:197], v[238:239], v[230:231], v[196:197]
	v_cvt_pk_bf16_f32 v195, v194, v195
	v_cvt_pk_bf16_f32 v194, v192, v193
	v_cvt_pk_bf16_f32 v199, v198, v199
	v_cvt_pk_bf16_f32 v198, v196, v197
	s_add_u32 s18, s100, 0xd0000
	s_addc_u32 s19, s101, 0
	global_store_dwordx2 v243, v[194:195], s[18:19]
	global_store_dwordx2 v243, v[198:199], s[18:19] offset:32
	s_add_u32 s18, s98, 0x140000
	s_addc_u32 s19, s99, 0
	global_load_dwordx4 v[168:171], v242, s[18:19]
	global_load_dwordx4 v[172:175], v242, s[18:19] offset:64
	s_add_u32 s18, s98, 0x160000
	s_addc_u32 s19, s99, 0
	global_load_dwordx4 v[176:179], v242, s[18:19]
	global_load_dwordx4 v[180:183], v242, s[18:19] offset:64
	s_add_u32 s18, s98, 0x1c0000
	s_addc_u32 s19, s99, 0
	global_load_dwordx4 v[184:187], v242, s[18:19]
	global_load_dwordx4 v[188:191], v242, s[18:19] offset:64
	s_add_u32 s18, s98, 0x1e0000
	s_addc_u32 s19, s99, 0
	global_load_dwordx4 v[192:195], v242, s[18:19]
	global_load_dwordx4 v[196:199], v242, s[18:19] offset:64
	s_barrier
	ds_write2_b32 v146, v8, v12 offset1:16
	ds_write2_b32 v104, v9, v13 offset0:4 offset1:20
	ds_write2_b32 v105, v10, v14 offset0:8 offset1:24
	ds_write2_b32 v106, v11, v15 offset0:12 offset1:28
	ds_write2_b32 v146, v24, v28 offset0:128 offset1:144
	ds_write2_b32 v104, v25, v29 offset0:132 offset1:148
	ds_write2_b32 v105, v26, v30 offset0:136 offset1:152
	ds_write2_b32 v106, v27, v31 offset0:140 offset1:156
	ds_write2_b32 v107, v0, v4 offset0:64 offset1:80
	ds_write2_b32 v108, v1, v5 offset0:68 offset1:84
	ds_write2_b32 v109, v2, v6 offset0:72 offset1:88
	ds_write2_b32 v110, v3, v7 offset0:76 offset1:92
	ds_write2_b32 v107, v16, v20 offset0:192 offset1:208
	ds_write2_b32 v108, v17, v21 offset0:196 offset1:212
	ds_write2_b32 v109, v18, v22 offset0:200 offset1:216
	ds_write2_b32 v110, v19, v23 offset0:204 offset1:220
	s_waitcnt lgkmcnt(0)
	s_barrier
	ds_read_b128 v[200:203], v244 offset:0
	ds_read_b128 v[204:207], v244 offset:64
	ds_read_b128 v[208:211], v244 offset:16640
	ds_read_b128 v[212:215], v244 offset:16704
	ds_read_b128 v[216:219], v244 offset:33280
	ds_read_b128 v[220:223], v244 offset:33344
	ds_read_b128 v[226:229], v244 offset:49920
	ds_read_b128 v[230:233], v244 offset:49984
	s_waitcnt vmcnt(0)
	s_waitcnt lgkmcnt(6)
	v_pk_fma_f32 v[170:171], v[236:237], v[202:203], v[170:171]
	v_pk_fma_f32 v[168:169], v[234:235], v[200:201], v[168:169]
	v_pk_fma_f32 v[174:175], v[240:241], v[206:207], v[174:175]
	v_pk_fma_f32 v[172:173], v[238:239], v[204:205], v[172:173]
	v_cvt_pk_bf16_f32 v171, v170, v171
	v_cvt_pk_bf16_f32 v170, v168, v169
	v_cvt_pk_bf16_f32 v175, v174, v175
	v_cvt_pk_bf16_f32 v174, v172, v173
	s_add_u32 s18, s100, 0xa0000
	s_addc_u32 s19, s101, 0
	global_store_dwordx2 v243, v[170:171], s[18:19]
	global_store_dwordx2 v243, v[174:175], s[18:19] offset:32
	s_waitcnt lgkmcnt(4)
	v_pk_fma_f32 v[178:179], v[236:237], v[210:211], v[178:179]
	v_pk_fma_f32 v[176:177], v[234:235], v[208:209], v[176:177]
	v_pk_fma_f32 v[182:183], v[240:241], v[214:215], v[182:183]
	v_pk_fma_f32 v[180:181], v[238:239], v[212:213], v[180:181]
	v_cvt_pk_bf16_f32 v179, v178, v179
	v_cvt_pk_bf16_f32 v178, v176, v177
	v_cvt_pk_bf16_f32 v183, v182, v183
	v_cvt_pk_bf16_f32 v182, v180, v181
	s_add_u32 s18, s100, 0xb0000
	s_addc_u32 s19, s101, 0
	global_store_dwordx2 v243, v[178:179], s[18:19]
	global_store_dwordx2 v243, v[182:183], s[18:19] offset:32
	s_waitcnt lgkmcnt(2)
	v_pk_fma_f32 v[186:187], v[236:237], v[218:219], v[186:187]
	v_pk_fma_f32 v[184:185], v[234:235], v[216:217], v[184:185]
	v_pk_fma_f32 v[190:191], v[240:241], v[222:223], v[190:191]
	v_pk_fma_f32 v[188:189], v[238:239], v[220:221], v[188:189]
	v_cvt_pk_bf16_f32 v187, v186, v187
	v_cvt_pk_bf16_f32 v186, v184, v185
	v_cvt_pk_bf16_f32 v191, v190, v191
	v_cvt_pk_bf16_f32 v190, v188, v189
	s_add_u32 s18, s100, 0xe0000
	s_addc_u32 s19, s101, 0
	global_store_dwordx2 v243, v[186:187], s[18:19]
	global_store_dwordx2 v243, v[190:191], s[18:19] offset:32
	s_waitcnt lgkmcnt(0)
	v_pk_fma_f32 v[194:195], v[236:237], v[228:229], v[194:195]
	v_pk_fma_f32 v[192:193], v[234:235], v[226:227], v[192:193]
	v_pk_fma_f32 v[198:199], v[240:241], v[232:233], v[198:199]
	v_pk_fma_f32 v[196:197], v[238:239], v[230:231], v[196:197]
	v_cvt_pk_bf16_f32 v195, v194, v195
	v_cvt_pk_bf16_f32 v194, v192, v193
	v_cvt_pk_bf16_f32 v199, v198, v199
	v_cvt_pk_bf16_f32 v198, v196, v197
	s_add_u32 s18, s100, 0xf0000
	s_addc_u32 s19, s101, 0
	global_store_dwordx2 v243, v[194:195], s[18:19]
	global_store_dwordx2 v243, v[198:199], s[18:19] offset:32
	s_add_i32 s66, s66, s84
	s_cmpk_lt_i32 s66, 0x100
	s_barrier
	s_cbranch_scc0 .LBB0_924

.LBB0_1152:
	v_and_b32_e32 v131, 0x7c, v129
	v_lshlrev_b32_e32 v129, 2, v131
	v_add_u32_e32 v141, s65, v129
	v_add_u32_e32 v142, s66, v129
	v_add_u32_e32 v143, s67, v129
	v_add_u32_e32 v144, s68, v129
	v_add_u32_e32 v145, s69, v129
	v_add_u32_e32 v146, s70, v129
	v_ashrrev_i32_e32 v129, 31, v128
	s_lshl_b64 s[18:19], s[20:21], 1
	v_lshl_add_u64 v[128:129], v[128:129], 1, s[14:15]
	v_lshlrev_b32_e32 v132, 1, v131
	v_mov_b32_e32 v133, v229
	v_ashrrev_i32_e32 v140, 5, v130
	s_add_u32 s18, s61, s18
	v_lshl_add_u64 v[136:137], v[128:129], 0, v[132:133]
	v_and_b32_e32 v129, 31, v130
	s_addc_u32 s19, s62, s19
	s_add_i32 s20, s25, s24
	v_mul_lo_u32 v128, v140, s71
	v_lshlrev_b32_e32 v129, 4, v129
	s_add_i32 s20, s20, s76
	v_add3_u32 v147, v128, v129, s72
	v_lshl_add_u64 v[138:139], s[18:19], 0, v[132:133]
	v_add_u32_e32 v165, s20, v140
	s_mov_b32 s21, 0
	v_mov_b32_e32 v166, v147
	s_waitcnt vmcnt(0) lgkmcnt(0)
	s_barrier
	ds_read_b128 v[184:187], v141
	ds_read_b128 v[188:191], v142
	ds_read_b128 v[192:195], v143
	ds_read_b128 v[196:199], v144
	ds_read_b128 v[200:203], v145
	ds_read_b128 v[204:207], v146
	s_branch .LBB0_1154

.LBB0_1156:
	s_or_b64 exec, exec, s[18:19]
	v_add_u32_e32 v168, -1, v168
	v_cmp_gt_u32_e32 vcc, 62, v168
	s_and_saveexec_b64 s[18:19], vcc
	s_cbranch_execz .LBB0_1153
	ds_read_b128 v[168:171], v166
	ds_read_b128 v[172:175], v166 offset:512
	ds_read_b128 v[176:179], v166 offset:2080
	ds_read_b128 v[180:183], v166 offset:2592
	s_waitcnt lgkmcnt(3)
	v_pk_mul_f32 v[134:135], v[134:135], v[190:191]
	v_pk_mul_f32 v[132:133], v[132:133], v[188:189]
	v_pk_fma_f32 v[134:135], v[170:171], v[186:187], v[134:135]
	v_pk_fma_f32 v[132:133], v[168:169], v[184:185], v[132:133]
	s_waitcnt lgkmcnt(1)
	v_pk_fma_f32 v[134:135], v[178:179], v[194:195], v[134:135]
	v_pk_fma_f32 v[132:133], v[176:177], v[192:193], v[132:133]
	v_mul_f32_e32 v170, 0xbfb8aa3b, v134
	v_mul_f32_e32 v168, 0xbfb8aa3b, v132
	v_mul_f32_e32 v169, 0xbfb8aa3b, v133
	v_mul_f32_e32 v171, 0xbfb8aa3b, v135
	v_exp_f32_e32 v168, v168
	v_exp_f32_e32 v169, v169
	v_exp_f32_e32 v170, v170
	v_exp_f32_e32 v171, v171
	v_add_f32_e32 v168, 1.0, v168
	v_add_f32_e32 v169, 1.0, v169
	v_add_f32_e32 v170, 1.0, v170
	v_add_f32_e32 v171, 1.0, v171
	v_rcp_f32_e32 v168, v168
	v_rcp_f32_e32 v169, v169
	v_rcp_f32_e32 v170, v170
	v_rcp_f32_e32 v171, v171
	s_waitcnt lgkmcnt(1)
	v_pk_mul_f32 v[130:131], v[130:131], v[202:203]
	v_pk_mul_f32 v[128:129], v[128:129], v[200:201]
	v_pk_fma_f32 v[130:131], v[174:175], v[198:199], v[130:131]
	v_pk_fma_f32 v[128:129], v[172:173], v[196:197], v[128:129]
	s_waitcnt lgkmcnt(0)
	v_pk_fma_f32 v[130:131], v[182:183], v[206:207], v[130:131]
	v_pk_fma_f32 v[128:129], v[180:181], v[204:205], v[128:129]
	v_pk_mul_f32 v[132:133], v[132:133], v[168:169]
	v_pk_mul_f32 v[134:135], v[134:135], v[170:171]
	v_pk_mul_f32 v[128:129], v[128:129], v[132:133]
	v_pk_mul_f32 v[130:131], v[130:131], v[134:135]
	s_nop 0
	v_cvt_pk_bf16_f32 v131, v130, v131
	v_cvt_pk_bf16_f32 v130, v128, v129
	v_mad_i64_i32 v[128:129], s[22:23], v167, s64, v[136:137]
	global_store_dwordx2 v[128:129], v[130:131], off
	s_branch .LBB0_1153

.LBB0_1164:
	s_or_b64 exec, exec, s[18:19]
	v_add_u32_e32 v75, -1, v75
	v_cmp_gt_u32_e32 vcc, 62, v75
	s_and_saveexec_b64 s[18:19], vcc
	s_cbranch_execz .LBB0_1161
	ds_read_b128 v[76:79], v73
	ds_read_b128 v[80:83], v73 offset:512
	ds_read_b128 v[84:87], v73 offset:2080
	ds_read_b128 v[88:91], v73 offset:2592
	s_waitcnt lgkmcnt(3)
	v_pk_mul_f32 v[68:69], v[68:69], v[188:189]
	v_pk_mul_f32 v[70:71], v[70:71], v[190:191]
	v_pk_fma_f32 v[68:69], v[76:77], v[184:185], v[68:69]
	v_pk_fma_f32 v[70:71], v[78:79], v[186:187], v[70:71]
	s_waitcnt lgkmcnt(1)
	v_pk_fma_f32 v[68:69], v[84:85], v[192:193], v[68:69]
	v_pk_fma_f32 v[70:71], v[86:87], v[194:195], v[70:71]
	v_mul_f32_e32 v75, 0xbfb8aa3b, v68
	v_exp_f32_e32 v75, v75
	v_mul_f32_e32 v76, 0xbfb8aa3b, v69
	v_exp_f32_e32 v77, v76
	s_waitcnt lgkmcnt(1)
	v_pk_mul_f32 v[66:67], v[66:67], v[202:203]
	v_add_f32_e32 v75, 1.0, v75
	v_rcp_f32_e32 v76, v75
	v_add_f32_e32 v75, 1.0, v77
	v_mul_f32_e32 v77, 0xbfb8aa3b, v70
	v_exp_f32_e32 v78, v77
	v_mul_f32_e32 v77, 0xbfb8aa3b, v71
	v_exp_f32_e32 v79, v77
	v_rcp_f32_e32 v77, v75
	v_add_f32_e32 v75, 1.0, v78
	v_rcp_f32_e32 v78, v75
	v_add_f32_e32 v75, 1.0, v79
	v_rcp_f32_e32 v79, v75
	v_pk_mul_f32 v[64:65], v[64:65], v[200:201]
	v_pk_fma_f32 v[66:67], v[82:83], v[198:199], v[66:67]
	v_pk_fma_f32 v[64:65], v[80:81], v[196:197], v[64:65]
	s_waitcnt lgkmcnt(0)
	v_pk_fma_f32 v[66:67], v[90:91], v[206:207], v[66:67]
	v_pk_fma_f32 v[64:65], v[88:89], v[204:205], v[64:65]
	v_pk_mul_f32 v[68:69], v[68:69], v[76:77]
	v_pk_mul_f32 v[70:71], v[70:71], v[78:79]
	v_pk_mul_f32 v[64:65], v[64:65], v[68:69]
	v_pk_mul_f32 v[66:67], v[66:67], v[70:71]
	s_nop 0
	v_cvt_pk_bf16_f32 v67, v66, v67
	v_cvt_pk_bf16_f32 v66, v64, v65
	v_mad_i64_i32 v[64:65], s[22:23], v74, s64, v[136:137]
	global_store_dwordx2 v[64:65], v[66:67], off
	s_branch .LBB0_1161

.LBB0_1173:
	s_or_b64 exec, exec, s[4:5]
	v_add_u32_e32 v75, -1, v75
	v_cmp_gt_u32_e32 vcc, 62, v75
	s_and_saveexec_b64 s[4:5], vcc
	s_cbranch_execz .LBB0_1170
	ds_read_b128 v[76:79], v73
	ds_read_b128 v[80:83], v73 offset:512
	ds_read_b128 v[84:87], v73 offset:2080
	ds_read_b128 v[88:91], v73 offset:2592
	s_waitcnt lgkmcnt(3)
	v_pk_mul_f32 v[68:69], v[68:69], v[188:189]
	v_pk_mul_f32 v[70:71], v[70:71], v[190:191]
	v_pk_fma_f32 v[68:69], v[76:77], v[184:185], v[68:69]
	v_pk_fma_f32 v[70:71], v[78:79], v[186:187], v[70:71]
	s_waitcnt lgkmcnt(1)
	v_pk_fma_f32 v[68:69], v[84:85], v[192:193], v[68:69]
	v_pk_fma_f32 v[70:71], v[86:87], v[194:195], v[70:71]
	v_mul_f32_e32 v75, 0xbfb8aa3b, v68
	v_exp_f32_e32 v75, v75
	v_mul_f32_e32 v76, 0xbfb8aa3b, v69
	v_exp_f32_e32 v77, v76
	s_waitcnt lgkmcnt(1)
	v_pk_mul_f32 v[66:67], v[66:67], v[202:203]
	v_add_f32_e32 v75, 1.0, v75
	v_rcp_f32_e32 v76, v75
	v_add_f32_e32 v75, 1.0, v77
	v_mul_f32_e32 v77, 0xbfb8aa3b, v70
	v_exp_f32_e32 v78, v77
	v_mul_f32_e32 v77, 0xbfb8aa3b, v71
	v_exp_f32_e32 v79, v77
	v_rcp_f32_e32 v77, v75
	v_add_f32_e32 v75, 1.0, v78
	v_rcp_f32_e32 v78, v75
	v_add_f32_e32 v75, 1.0, v79
	v_rcp_f32_e32 v79, v75
	v_pk_mul_f32 v[64:65], v[64:65], v[200:201]
	v_pk_fma_f32 v[66:67], v[82:83], v[198:199], v[66:67]
	v_pk_fma_f32 v[64:65], v[80:81], v[196:197], v[64:65]
	s_waitcnt lgkmcnt(0)
	v_pk_fma_f32 v[66:67], v[90:91], v[206:207], v[66:67]
	v_pk_fma_f32 v[64:65], v[88:89], v[204:205], v[64:65]
	v_pk_mul_f32 v[68:69], v[68:69], v[76:77]
	v_pk_mul_f32 v[70:71], v[70:71], v[78:79]
	v_pk_mul_f32 v[64:65], v[64:65], v[68:69]
	v_pk_mul_f32 v[66:67], v[66:67], v[70:71]
	s_nop 0
	v_cvt_pk_bf16_f32 v67, v66, v67
	v_cvt_pk_bf16_f32 v66, v64, v65
	v_mad_i64_i32 v[64:65], s[18:19], v74, s64, v[136:137]
	global_store_dwordx2 v[64:65], v[66:67], off
	s_branch .LBB0_1170

.LBB0_1181:
	s_or_b64 exec, exec, s[2:3]
	v_add_u32_e32 v10, -1, v10
	v_cmp_gt_u32_e32 vcc, 62, v10
	s_and_saveexec_b64 s[2:3], vcc
	s_cbranch_execz .LBB0_1178
	ds_read_b128 v[10:13], v147
	ds_read_b128 v[14:17], v147 offset:512
	ds_read_b128 v[18:21], v147 offset:2080
	ds_read_b128 v[22:25], v147 offset:2592
	s_waitcnt lgkmcnt(3)
	v_pk_mul_f32 v[6:7], v[6:7], v[190:191]
	v_pk_mul_f32 v[4:5], v[4:5], v[188:189]
	v_pk_fma_f32 v[6:7], v[12:13], v[186:187], v[6:7]
	v_pk_fma_f32 v[4:5], v[10:11], v[184:185], v[4:5]
	s_waitcnt lgkmcnt(1)
	v_pk_fma_f32 v[6:7], v[20:21], v[194:195], v[6:7]
	v_pk_fma_f32 v[4:5], v[18:19], v[192:193], v[4:5]
	v_mul_f32_e32 v12, 0xbfb8aa3b, v6
	v_mul_f32_e32 v10, 0xbfb8aa3b, v4
	v_mul_f32_e32 v11, 0xbfb8aa3b, v5
	v_mul_f32_e32 v13, 0xbfb8aa3b, v7
	v_exp_f32_e32 v10, v10
	v_exp_f32_e32 v11, v11
	v_exp_f32_e32 v12, v12
	v_exp_f32_e32 v13, v13
	v_add_f32_e32 v10, 1.0, v10
	v_add_f32_e32 v11, 1.0, v11
	v_add_f32_e32 v12, 1.0, v12
	v_add_f32_e32 v13, 1.0, v13
	v_rcp_f32_e32 v10, v10
	v_rcp_f32_e32 v11, v11
	v_rcp_f32_e32 v12, v12
	v_rcp_f32_e32 v13, v13
	s_waitcnt lgkmcnt(1)
	v_pk_mul_f32 v[2:3], v[2:3], v[202:203]
	v_pk_mul_f32 v[0:1], v[0:1], v[200:201]
	v_pk_fma_f32 v[2:3], v[16:17], v[198:199], v[2:3]
	v_pk_fma_f32 v[0:1], v[14:15], v[196:197], v[0:1]
	s_waitcnt lgkmcnt(0)
	v_pk_fma_f32 v[2:3], v[24:25], v[206:207], v[2:3]
	v_pk_fma_f32 v[0:1], v[22:23], v[204:205], v[0:1]
	v_pk_mul_f32 v[4:5], v[4:5], v[10:11]
	v_pk_mul_f32 v[6:7], v[6:7], v[12:13]
	v_pk_mul_f32 v[0:1], v[0:1], v[4:5]
	v_pk_mul_f32 v[2:3], v[2:3], v[6:7]
	s_nop 0
	v_cvt_pk_bf16_f32 v3, v2, v3
	v_cvt_pk_bf16_f32 v2, v0, v1
	v_mad_i64_i32 v[0:1], s[6:7], v9, s64, v[136:137]
	global_store_dwordx2 v[0:1], v[2:3], off
	s_branch .LBB0_1178

.LBB0_1463:
	s_add_i32 s24, s53, 0xfffff000
	s_lshr_b32 s25, s24, 10
	s_mulk_i32 s25, 0x3000
	s_cmp_lt_u32 s53, 0x1000
	s_cselect_b32 s25, 0xc000, s25
	s_lshl_b32 s24, s53, 12
	s_add_u32 s100, s6, s24
	s_addc_u32 s101, s7, 0
	s_lshl_b32 s25, s25, 2
	s_add_u32 s24, s28, s25
	s_addc_u32 s25, s29, 0
	s_add_u32 s24, s24, 0x163ca000
	s_addc_u32 s25, s25, 0
	s_lshl_b32 s99, s38, 8
	v_lshlrev_b32_e32 v246, 3, v224
	v_lshlrev_b32_e32 v247, 2, v224
	v_and_b32_e32 v246, 0xe0, v246
	v_and_b32_e32 v247, 12, v247
	v_or_b32_e32 v246, v246, v247
	v_lshrrev_b32_e32 v247, 5, v224
	v_or_b32_e32 v248, s99, v246
	v_lshlrev_b32_e32 v245, 2, v248
	v_lshlrev_b32_e32 v248, 1, v248
	v_lshl_add_u32 v243, v247, 12, v248
	v_mul_u32_u24_e32 v247, 0x410, v247
	v_lshl_add_u32 v244, v246, 2, v247
	v_add_u32_e32 v244, 16, v244
	global_load_dwordx4 v[234:237], v245, s[24:25]
	global_load_dwordx4 v[238:241], v245, s[24:25] offset:64
	global_load_dwordx2 v[168:169], v243, s[100:101]
	global_load_dwordx2 v[170:171], v243, s[100:101] offset:32
	s_add_u32 s24, s100, 0x10000
	s_addc_u32 s25, s101, 0
	global_load_dwordx2 v[172:173], v243, s[24:25]
	global_load_dwordx2 v[174:175], v243, s[24:25] offset:32
	s_add_u32 s24, s100, 0x40000
	s_addc_u32 s25, s101, 0
	global_load_dwordx2 v[176:177], v243, s[24:25]
	global_load_dwordx2 v[178:179], v243, s[24:25] offset:32
	s_add_u32 s24, s100, 0x50000
	s_addc_u32 s25, s101, 0
	global_load_dwordx2 v[180:181], v243, s[24:25]
	global_load_dwordx2 v[182:183], v243, s[24:25] offset:32
	ds_write2_b32 v140, v104, v108 offset1:16
	v_add_u32_e32 v104, 0x400, v140
	ds_write2_b32 v104, v105, v109 offset0:4 offset1:20
	v_add_u32_e32 v105, 0x800, v140
	ds_write2_b32 v105, v106, v110 offset0:8 offset1:24
	v_add_u32_e32 v106, 0xc00, v140
	ds_write2_b32 v106, v107, v111 offset0:12 offset1:28
	ds_write2_b32 v140, v120, v124 offset0:128 offset1:144
	ds_write2_b32 v104, v121, v125 offset0:132 offset1:148
	ds_write2_b32 v105, v122, v126 offset0:136 offset1:152
	ds_write2_b32 v106, v123, v127 offset0:140 offset1:156
	v_add_u32_e32 v107, 0x4000, v140
	ds_write2_b32 v107, v96, v100 offset0:64 offset1:80
	v_add_u32_e32 v108, 0x4400, v140
	v_add_u32_e32 v109, 0x4800, v140
	v_add_u32_e32 v110, 0x4c00, v140
	v_mov_b32_e32 v96, v224
	s_add_i32 s19, s53, 0xfffff000
	s_lshl_b32 s18, s38, 8
	ds_write2_b32 v108, v97, v101 offset0:68 offset1:84
	ds_write2_b32 v109, v98, v102 offset0:72 offset1:88
	ds_write2_b32 v110, v99, v103 offset0:76 offset1:92
	ds_write2_b32 v107, v112, v116 offset0:192 offset1:208
	ds_write2_b32 v108, v113, v117 offset0:196 offset1:212
	ds_write2_b32 v109, v114, v118 offset0:200 offset1:216
	ds_write2_b32 v110, v115, v119 offset0:204 offset1:220
	s_waitcnt lgkmcnt(0)
	s_barrier
	ds_read_b128 v[200:203], v244 offset:0
	ds_read_b128 v[204:207], v244 offset:64
	ds_read_b128 v[208:211], v244 offset:16640
	ds_read_b128 v[212:215], v244 offset:16704
	ds_read_b128 v[216:219], v244 offset:33280
	ds_read_b128 v[220:223], v244 offset:33344
	ds_read_b128 v[226:229], v244 offset:49920
	ds_read_b128 v[230:233], v244 offset:49984
	s_waitcnt vmcnt(0)
	v_lshlrev_b32_e32 v184, 16, v168
	v_and_b32_e32 v185, 0xffff0000, v168
	v_lshlrev_b32_e32 v186, 16, v169
	v_and_b32_e32 v187, 0xffff0000, v169
	v_lshlrev_b32_e32 v188, 16, v170
	v_and_b32_e32 v189, 0xffff0000, v170
	v_lshlrev_b32_e32 v190, 16, v171
	v_and_b32_e32 v191, 0xffff0000, v171
	s_waitcnt lgkmcnt(6)
	v_pk_fma_f32 v[186:187], v[236:237], v[202:203], v[186:187]
	v_pk_fma_f32 v[184:185], v[234:235], v[200:201], v[184:185]
	v_pk_fma_f32 v[190:191], v[240:241], v[206:207], v[190:191]
	v_pk_fma_f32 v[188:189], v[238:239], v[204:205], v[188:189]
	v_cvt_pk_bf16_f32 v187, v186, v187
	v_cvt_pk_bf16_f32 v186, v184, v185
	v_cvt_pk_bf16_f32 v191, v190, v191
	v_cvt_pk_bf16_f32 v190, v188, v189
	global_store_dwordx2 v243, v[186:187], s[100:101]
	global_store_dwordx2 v243, v[190:191], s[100:101] offset:32
	v_lshlrev_b32_e32 v192, 16, v172
	v_and_b32_e32 v193, 0xffff0000, v172
	v_lshlrev_b32_e32 v194, 16, v173
	v_and_b32_e32 v195, 0xffff0000, v173
	v_lshlrev_b32_e32 v196, 16, v174
	v_and_b32_e32 v197, 0xffff0000, v174
	v_lshlrev_b32_e32 v198, 16, v175
	v_and_b32_e32 v199, 0xffff0000, v175
	s_waitcnt lgkmcnt(4)
	v_pk_fma_f32 v[194:195], v[236:237], v[210:211], v[194:195]
	v_pk_fma_f32 v[192:193], v[234:235], v[208:209], v[192:193]
	v_pk_fma_f32 v[198:199], v[240:241], v[214:215], v[198:199]
	v_pk_fma_f32 v[196:197], v[238:239], v[212:213], v[196:197]
	v_cvt_pk_bf16_f32 v195, v194, v195
	v_cvt_pk_bf16_f32 v194, v192, v193
	v_cvt_pk_bf16_f32 v199, v198, v199
	v_cvt_pk_bf16_f32 v198, v196, v197
	s_add_u32 s24, s100, 0x10000
	s_addc_u32 s25, s101, 0
	global_store_dwordx2 v243, v[194:195], s[24:25]
	global_store_dwordx2 v243, v[198:199], s[24:25] offset:32
	v_lshlrev_b32_e32 v184, 16, v176
	v_and_b32_e32 v185, 0xffff0000, v176
	v_lshlrev_b32_e32 v186, 16, v177
	v_and_b32_e32 v187, 0xffff0000, v177
	v_lshlrev_b32_e32 v188, 16, v178
	v_and_b32_e32 v189, 0xffff0000, v178
	v_lshlrev_b32_e32 v190, 16, v179
	v_and_b32_e32 v191, 0xffff0000, v179
	s_waitcnt lgkmcnt(2)
	v_pk_fma_f32 v[186:187], v[236:237], v[218:219], v[186:187]
	v_pk_fma_f32 v[184:185], v[234:235], v[216:217], v[184:185]
	v_pk_fma_f32 v[190:191], v[240:241], v[222:223], v[190:191]
	v_pk_fma_f32 v[188:189], v[238:239], v[220:221], v[188:189]
	v_cvt_pk_bf16_f32 v187, v186, v187
	v_cvt_pk_bf16_f32 v186, v184, v185
	v_cvt_pk_bf16_f32 v191, v190, v191
	v_cvt_pk_bf16_f32 v190, v188, v189
	s_add_u32 s24, s100, 0x40000
	s_addc_u32 s25, s101, 0
	global_store_dwordx2 v243, v[186:187], s[24:25]
	global_store_dwordx2 v243, v[190:191], s[24:25] offset:32
	v_lshlrev_b32_e32 v192, 16, v180
	v_and_b32_e32 v193, 0xffff0000, v180
	v_lshlrev_b32_e32 v194, 16, v181
	v_and_b32_e32 v195, 0xffff0000, v181
	v_lshlrev_b32_e32 v196, 16, v182
	v_and_b32_e32 v197, 0xffff0000, v182
	v_lshlrev_b32_e32 v198, 16, v183
	v_and_b32_e32 v199, 0xffff0000, v183
	s_waitcnt lgkmcnt(0)
	v_pk_fma_f32 v[194:195], v[236:237], v[228:229], v[194:195]
	v_pk_fma_f32 v[192:193], v[234:235], v[226:227], v[192:193]
	v_pk_fma_f32 v[198:199], v[240:241], v[232:233], v[198:199]
	v_pk_fma_f32 v[196:197], v[238:239], v[230:231], v[196:197]
	v_cvt_pk_bf16_f32 v195, v194, v195
	v_cvt_pk_bf16_f32 v194, v192, v193
	v_cvt_pk_bf16_f32 v199, v198, v199
	v_cvt_pk_bf16_f32 v198, v196, v197
	s_add_u32 s24, s100, 0x50000
	s_addc_u32 s25, s101, 0
	global_store_dwordx2 v243, v[194:195], s[24:25]
	global_store_dwordx2 v243, v[198:199], s[24:25] offset:32
	s_add_u32 s24, s100, 0x20000
	s_addc_u32 s25, s101, 0
	global_load_dwordx2 v[168:169], v243, s[24:25]
	global_load_dwordx2 v[170:171], v243, s[24:25] offset:32
	s_add_u32 s24, s100, 0x30000
	s_addc_u32 s25, s101, 0
	global_load_dwordx2 v[172:173], v243, s[24:25]
	global_load_dwordx2 v[174:175], v243, s[24:25] offset:32
	s_add_u32 s24, s100, 0x60000
	s_addc_u32 s25, s101, 0
	global_load_dwordx2 v[176:177], v243, s[24:25]
	global_load_dwordx2 v[178:179], v243, s[24:25] offset:32
	s_add_u32 s24, s100, 0x70000
	s_addc_u32 s25, s101, 0
	global_load_dwordx2 v[180:181], v243, s[24:25]
	global_load_dwordx2 v[182:183], v243, s[24:25] offset:32
	s_barrier
	ds_write2_b32 v140, v72, v76 offset1:16
	ds_write2_b32 v104, v73, v77 offset0:4 offset1:20
	ds_write2_b32 v105, v74, v78 offset0:8 offset1:24
	ds_write2_b32 v106, v75, v79 offset0:12 offset1:28
	ds_write2_b32 v140, v88, v92 offset0:128 offset1:144
	ds_write2_b32 v104, v89, v93 offset0:132 offset1:148
	ds_write2_b32 v105, v90, v94 offset0:136 offset1:152
	ds_write2_b32 v106, v91, v95 offset0:140 offset1:156
	ds_write2_b32 v107, v64, v68 offset0:64 offset1:80
	ds_write2_b32 v108, v65, v69 offset0:68 offset1:84
	ds_write2_b32 v109, v66, v70 offset0:72 offset1:88
	ds_write2_b32 v110, v67, v71 offset0:76 offset1:92
	ds_write2_b32 v107, v80, v84 offset0:192 offset1:208
	ds_write2_b32 v108, v81, v85 offset0:196 offset1:212
	ds_write2_b32 v109, v82, v86 offset0:200 offset1:216
	ds_write2_b32 v110, v83, v87 offset0:204 offset1:220
	s_waitcnt lgkmcnt(0)
	s_barrier
	ds_read_b128 v[200:203], v244 offset:0
	ds_read_b128 v[204:207], v244 offset:64
	ds_read_b128 v[208:211], v244 offset:16640
	ds_read_b128 v[212:215], v244 offset:16704
	ds_read_b128 v[216:219], v244 offset:33280
	ds_read_b128 v[220:223], v244 offset:33344
	ds_read_b128 v[226:229], v244 offset:49920
	ds_read_b128 v[230:233], v244 offset:49984
	s_waitcnt vmcnt(0)
	v_lshlrev_b32_e32 v184, 16, v168
	v_and_b32_e32 v185, 0xffff0000, v168
	v_lshlrev_b32_e32 v186, 16, v169
	v_and_b32_e32 v187, 0xffff0000, v169
	v_lshlrev_b32_e32 v188, 16, v170
	v_and_b32_e32 v189, 0xffff0000, v170
	v_lshlrev_b32_e32 v190, 16, v171
	v_and_b32_e32 v191, 0xffff0000, v171
	s_waitcnt lgkmcnt(6)
	v_pk_fma_f32 v[186:187], v[236:237], v[202:203], v[186:187]
	v_pk_fma_f32 v[184:185], v[234:235], v[200:201], v[184:185]
	v_pk_fma_f32 v[190:191], v[240:241], v[206:207], v[190:191]
	v_pk_fma_f32 v[188:189], v[238:239], v[204:205], v[188:189]
	v_cvt_pk_bf16_f32 v187, v186, v187
	v_cvt_pk_bf16_f32 v186, v184, v185
	v_cvt_pk_bf16_f32 v191, v190, v191
	v_cvt_pk_bf16_f32 v190, v188, v189
	s_add_u32 s24, s100, 0x20000
	s_addc_u32 s25, s101, 0
	global_store_dwordx2 v243, v[186:187], s[24:25]
	global_store_dwordx2 v243, v[190:191], s[24:25] offset:32
	v_lshlrev_b32_e32 v192, 16, v172
	v_and_b32_e32 v193, 0xffff0000, v172
	v_lshlrev_b32_e32 v194, 16, v173
	v_and_b32_e32 v195, 0xffff0000, v173
	v_lshlrev_b32_e32 v196, 16, v174
	v_and_b32_e32 v197, 0xffff0000, v174
	v_lshlrev_b32_e32 v198, 16, v175
	v_and_b32_e32 v199, 0xffff0000, v175
	s_waitcnt lgkmcnt(4)
	v_pk_fma_f32 v[194:195], v[236:237], v[210:211], v[194:195]
	v_pk_fma_f32 v[192:193], v[234:235], v[208:209], v[192:193]
	v_pk_fma_f32 v[198:199], v[240:241], v[214:215], v[198:199]
	v_pk_fma_f32 v[196:197], v[238:239], v[212:213], v[196:197]
	v_cvt_pk_bf16_f32 v195, v194, v195
	v_cvt_pk_bf16_f32 v194, v192, v193
	v_cvt_pk_bf16_f32 v199, v198, v199
	v_cvt_pk_bf16_f32 v198, v196, v197
	s_add_u32 s24, s100, 0x30000
	s_addc_u32 s25, s101, 0
	global_store_dwordx2 v243, v[194:195], s[24:25]
	global_store_dwordx2 v243, v[198:199], s[24:25] offset:32
	v_lshlrev_b32_e32 v184, 16, v176
	v_and_b32_e32 v185, 0xffff0000, v176
	v_lshlrev_b32_e32 v186, 16, v177
	v_and_b32_e32 v187, 0xffff0000, v177
	v_lshlrev_b32_e32 v188, 16, v178
	v_and_b32_e32 v189, 0xffff0000, v178
	v_lshlrev_b32_e32 v190, 16, v179
	v_and_b32_e32 v191, 0xffff0000, v179
	s_waitcnt lgkmcnt(2)
	v_pk_fma_f32 v[186:187], v[236:237], v[218:219], v[186:187]
	v_pk_fma_f32 v[184:185], v[234:235], v[216:217], v[184:185]
	v_pk_fma_f32 v[190:191], v[240:241], v[222:223], v[190:191]
	v_pk_fma_f32 v[188:189], v[238:239], v[220:221], v[188:189]
	v_cvt_pk_bf16_f32 v187, v186, v187
	v_cvt_pk_bf16_f32 v186, v184, v185
	v_cvt_pk_bf16_f32 v191, v190, v191
	v_cvt_pk_bf16_f32 v190, v188, v189
	s_add_u32 s24, s100, 0x60000
	s_addc_u32 s25, s101, 0
	global_store_dwordx2 v243, v[186:187], s[24:25]
	global_store_dwordx2 v243, v[190:191], s[24:25] offset:32
	v_lshlrev_b32_e32 v192, 16, v180
	v_and_b32_e32 v193, 0xffff0000, v180
	v_lshlrev_b32_e32 v194, 16, v181
	v_and_b32_e32 v195, 0xffff0000, v181
	v_lshlrev_b32_e32 v196, 16, v182
	v_and_b32_e32 v197, 0xffff0000, v182
	v_lshlrev_b32_e32 v198, 16, v183
	v_and_b32_e32 v199, 0xffff0000, v183
	s_waitcnt lgkmcnt(0)
	v_pk_fma_f32 v[194:195], v[236:237], v[228:229], v[194:195]
	v_pk_fma_f32 v[192:193], v[234:235], v[226:227], v[192:193]
	v_pk_fma_f32 v[198:199], v[240:241], v[232:233], v[198:199]
	v_pk_fma_f32 v[196:197], v[238:239], v[230:231], v[196:197]
	v_cvt_pk_bf16_f32 v195, v194, v195
	v_cvt_pk_bf16_f32 v194, v192, v193
	v_cvt_pk_bf16_f32 v199, v198, v199
	v_cvt_pk_bf16_f32 v198, v196, v197
	s_add_u32 s24, s100, 0x70000
	s_addc_u32 s25, s101, 0
	global_store_dwordx2 v243, v[194:195], s[24:25]
	global_store_dwordx2 v243, v[198:199], s[24:25] offset:32
	s_add_u32 s24, s100, 0x80000
	s_addc_u32 s25, s101, 0
	global_load_dwordx2 v[168:169], v243, s[24:25]
	global_load_dwordx2 v[170:171], v243, s[24:25] offset:32
	s_add_u32 s24, s100, 0x90000
	s_addc_u32 s25, s101, 0
	global_load_dwordx2 v[172:173], v243, s[24:25]
	global_load_dwordx2 v[174:175], v243, s[24:25] offset:32
	s_add_u32 s24, s100, 0xc0000
	s_addc_u32 s25, s101, 0
	global_load_dwordx2 v[176:177], v243, s[24:25]
	global_load_dwordx2 v[178:179], v243, s[24:25] offset:32
	s_add_u32 s24, s100, 0xd0000
	s_addc_u32 s25, s101, 0
	global_load_dwordx2 v[180:181], v243, s[24:25]
	global_load_dwordx2 v[182:183], v243, s[24:25] offset:32
	s_barrier
	ds_write2_b32 v140, v40, v44 offset1:16
	ds_write2_b32 v104, v41, v45 offset0:4 offset1:20
	ds_write2_b32 v105, v42, v46 offset0:8 offset1:24
	ds_write2_b32 v106, v43, v47 offset0:12 offset1:28
	ds_write2_b32 v140, v56, v60 offset0:128 offset1:144
	ds_write2_b32 v104, v57, v61 offset0:132 offset1:148
	ds_write2_b32 v105, v58, v62 offset0:136 offset1:152
	ds_write2_b32 v106, v59, v63 offset0:140 offset1:156
	ds_write2_b32 v107, v32, v36 offset0:64 offset1:80
	ds_write2_b32 v108, v33, v37 offset0:68 offset1:84
	ds_write2_b32 v109, v34, v38 offset0:72 offset1:88
	ds_write2_b32 v110, v35, v39 offset0:76 offset1:92
	ds_write2_b32 v107, v48, v52 offset0:192 offset1:208
	ds_write2_b32 v108, v49, v53 offset0:196 offset1:212
	ds_write2_b32 v109, v50, v54 offset0:200 offset1:216
	ds_write2_b32 v110, v51, v55 offset0:204 offset1:220
	s_waitcnt lgkmcnt(0)
	s_barrier
	ds_read_b128 v[200:203], v244 offset:0
	ds_read_b128 v[204:207], v244 offset:64
	ds_read_b128 v[208:211], v244 offset:16640
	ds_read_b128 v[212:215], v244 offset:16704
	ds_read_b128 v[216:219], v244 offset:33280
	ds_read_b128 v[220:223], v244 offset:33344
	ds_read_b128 v[226:229], v244 offset:49920
	ds_read_b128 v[230:233], v244 offset:49984
	s_waitcnt vmcnt(0)
	v_lshlrev_b32_e32 v184, 16, v168
	v_and_b32_e32 v185, 0xffff0000, v168
	v_lshlrev_b32_e32 v186, 16, v169
	v_and_b32_e32 v187, 0xffff0000, v169
	v_lshlrev_b32_e32 v188, 16, v170
	v_and_b32_e32 v189, 0xffff0000, v170
	v_lshlrev_b32_e32 v190, 16, v171
	v_and_b32_e32 v191, 0xffff0000, v171
	s_waitcnt lgkmcnt(6)
	v_pk_fma_f32 v[186:187], v[236:237], v[202:203], v[186:187]
	v_pk_fma_f32 v[184:185], v[234:235], v[200:201], v[184:185]
	v_pk_fma_f32 v[190:191], v[240:241], v[206:207], v[190:191]
	v_pk_fma_f32 v[188:189], v[238:239], v[204:205], v[188:189]
	v_cvt_pk_bf16_f32 v187, v186, v187
	v_cvt_pk_bf16_f32 v186, v184, v185
	v_cvt_pk_bf16_f32 v191, v190, v191
	v_cvt_pk_bf16_f32 v190, v188, v189
	s_add_u32 s24, s100, 0x80000
	s_addc_u32 s25, s101, 0
	global_store_dwordx2 v243, v[186:187], s[24:25]
	global_store_dwordx2 v243, v[190:191], s[24:25] offset:32
	v_lshlrev_b32_e32 v192, 16, v172
	v_and_b32_e32 v193, 0xffff0000, v172
	v_lshlrev_b32_e32 v194, 16, v173
	v_and_b32_e32 v195, 0xffff0000, v173
	v_lshlrev_b32_e32 v196, 16, v174
	v_and_b32_e32 v197, 0xffff0000, v174
	v_lshlrev_b32_e32 v198, 16, v175
	v_and_b32_e32 v199, 0xffff0000, v175
	s_waitcnt lgkmcnt(4)
	v_pk_fma_f32 v[194:195], v[236:237], v[210:211], v[194:195]
	v_pk_fma_f32 v[192:193], v[234:235], v[208:209], v[192:193]
	v_pk_fma_f32 v[198:199], v[240:241], v[214:215], v[198:199]
	v_pk_fma_f32 v[196:197], v[238:239], v[212:213], v[196:197]
	v_cvt_pk_bf16_f32 v195, v194, v195
	v_cvt_pk_bf16_f32 v194, v192, v193
	v_cvt_pk_bf16_f32 v199, v198, v199
	v_cvt_pk_bf16_f32 v198, v196, v197
	s_add_u32 s24, s100, 0x90000
	s_addc_u32 s25, s101, 0
	global_store_dwordx2 v243, v[194:195], s[24:25]
	global_store_dwordx2 v243, v[198:199], s[24:25] offset:32
	v_lshlrev_b32_e32 v184, 16, v176
	v_and_b32_e32 v185, 0xffff0000, v176
	v_lshlrev_b32_e32 v186, 16, v177
	v_and_b32_e32 v187, 0xffff0000, v177
	v_lshlrev_b32_e32 v188, 16, v178
	v_and_b32_e32 v189, 0xffff0000, v178
	v_lshlrev_b32_e32 v190, 16, v179
	v_and_b32_e32 v191, 0xffff0000, v179
	s_waitcnt lgkmcnt(2)
	v_pk_fma_f32 v[186:187], v[236:237], v[218:219], v[186:187]
	v_pk_fma_f32 v[184:185], v[234:235], v[216:217], v[184:185]
	v_pk_fma_f32 v[190:191], v[240:241], v[222:223], v[190:191]
	v_pk_fma_f32 v[188:189], v[238:239], v[220:221], v[188:189]
	v_cvt_pk_bf16_f32 v187, v186, v187
	v_cvt_pk_bf16_f32 v186, v184, v185
	v_cvt_pk_bf16_f32 v191, v190, v191
	v_cvt_pk_bf16_f32 v190, v188, v189
	s_add_u32 s24, s100, 0xc0000
	s_addc_u32 s25, s101, 0
	global_store_dwordx2 v243, v[186:187], s[24:25]
	global_store_dwordx2 v243, v[190:191], s[24:25] offset:32
	v_lshlrev_b32_e32 v192, 16, v180
	v_and_b32_e32 v193, 0xffff0000, v180
	v_lshlrev_b32_e32 v194, 16, v181
	v_and_b32_e32 v195, 0xffff0000, v181
	v_lshlrev_b32_e32 v196, 16, v182
	v_and_b32_e32 v197, 0xffff0000, v182
	v_lshlrev_b32_e32 v198, 16, v183
	v_and_b32_e32 v199, 0xffff0000, v183
	s_waitcnt lgkmcnt(0)
	v_pk_fma_f32 v[194:195], v[236:237], v[228:229], v[194:195]
	v_pk_fma_f32 v[192:193], v[234:235], v[226:227], v[192:193]
	v_pk_fma_f32 v[198:199], v[240:241], v[232:233], v[198:199]
	v_pk_fma_f32 v[196:197], v[238:239], v[230:231], v[196:197]
	v_cvt_pk_bf16_f32 v195, v194, v195
	v_cvt_pk_bf16_f32 v194, v192, v193
	v_cvt_pk_bf16_f32 v199, v198, v199
	v_cvt_pk_bf16_f32 v198, v196, v197
	s_add_u32 s24, s100, 0xd0000
	s_addc_u32 s25, s101, 0
	global_store_dwordx2 v243, v[194:195], s[24:25]
	global_store_dwordx2 v243, v[198:199], s[24:25] offset:32
	s_add_u32 s24, s100, 0xa0000
	s_addc_u32 s25, s101, 0
	global_load_dwordx2 v[168:169], v243, s[24:25]
	global_load_dwordx2 v[170:171], v243, s[24:25] offset:32
	s_add_u32 s24, s100, 0xb0000
	s_addc_u32 s25, s101, 0
	global_load_dwordx2 v[172:173], v243, s[24:25]
	global_load_dwordx2 v[174:175], v243, s[24:25] offset:32
	s_add_u32 s24, s100, 0xe0000
	s_addc_u32 s25, s101, 0
	global_load_dwordx2 v[176:177], v243, s[24:25]
	global_load_dwordx2 v[178:179], v243, s[24:25] offset:32
	s_add_u32 s24, s100, 0xf0000
	s_addc_u32 s25, s101, 0
	global_load_dwordx2 v[180:181], v243, s[24:25]
	global_load_dwordx2 v[182:183], v243, s[24:25] offset:32
	s_barrier
	ds_write2_b32 v140, v8, v12 offset1:16
	ds_write2_b32 v104, v9, v13 offset0:4 offset1:20
	ds_write2_b32 v105, v10, v14 offset0:8 offset1:24
	ds_write2_b32 v106, v11, v15 offset0:12 offset1:28
	ds_write2_b32 v140, v24, v28 offset0:128 offset1:144
	ds_write2_b32 v104, v25, v29 offset0:132 offset1:148
	ds_write2_b32 v105, v26, v30 offset0:136 offset1:152
	ds_write2_b32 v106, v27, v31 offset0:140 offset1:156
	ds_write2_b32 v107, v0, v4 offset0:64 offset1:80
	ds_write2_b32 v108, v1, v5 offset0:68 offset1:84
	ds_write2_b32 v109, v2, v6 offset0:72 offset1:88
	ds_write2_b32 v110, v3, v7 offset0:76 offset1:92
	ds_write2_b32 v107, v16, v20 offset0:192 offset1:208
	ds_write2_b32 v108, v17, v21 offset0:196 offset1:212
	ds_write2_b32 v109, v18, v22 offset0:200 offset1:216
	ds_write2_b32 v110, v19, v23 offset0:204 offset1:220
	s_waitcnt lgkmcnt(0)
	s_barrier
	ds_read_b128 v[200:203], v244 offset:0
	ds_read_b128 v[204:207], v244 offset:64
	ds_read_b128 v[208:211], v244 offset:16640
	ds_read_b128 v[212:215], v244 offset:16704
	ds_read_b128 v[216:219], v244 offset:33280
	ds_read_b128 v[220:223], v244 offset:33344
	ds_read_b128 v[226:229], v244 offset:49920
	ds_read_b128 v[230:233], v244 offset:49984
	s_waitcnt vmcnt(0)
	v_lshlrev_b32_e32 v184, 16, v168
	v_and_b32_e32 v185, 0xffff0000, v168
	v_lshlrev_b32_e32 v186, 16, v169
	v_and_b32_e32 v187, 0xffff0000, v169
	v_lshlrev_b32_e32 v188, 16, v170
	v_and_b32_e32 v189, 0xffff0000, v170
	v_lshlrev_b32_e32 v190, 16, v171
	v_and_b32_e32 v191, 0xffff0000, v171
	s_waitcnt lgkmcnt(6)
	v_pk_fma_f32 v[186:187], v[236:237], v[202:203], v[186:187]
	v_pk_fma_f32 v[184:185], v[234:235], v[200:201], v[184:185]
	v_pk_fma_f32 v[190:191], v[240:241], v[206:207], v[190:191]
	v_pk_fma_f32 v[188:189], v[238:239], v[204:205], v[188:189]
	v_cvt_pk_bf16_f32 v187, v186, v187
	v_cvt_pk_bf16_f32 v186, v184, v185
	v_cvt_pk_bf16_f32 v191, v190, v191
	v_cvt_pk_bf16_f32 v190, v188, v189
	s_add_u32 s24, s100, 0xa0000
	s_addc_u32 s25, s101, 0
	global_store_dwordx2 v243, v[186:187], s[24:25]
	global_store_dwordx2 v243, v[190:191], s[24:25] offset:32
	v_lshlrev_b32_e32 v192, 16, v172
	v_and_b32_e32 v193, 0xffff0000, v172
	v_lshlrev_b32_e32 v194, 16, v173
	v_and_b32_e32 v195, 0xffff0000, v173
	v_lshlrev_b32_e32 v196, 16, v174
	v_and_b32_e32 v197, 0xffff0000, v174
	v_lshlrev_b32_e32 v198, 16, v175
	v_and_b32_e32 v199, 0xffff0000, v175
	s_waitcnt lgkmcnt(4)
	v_pk_fma_f32 v[194:195], v[236:237], v[210:211], v[194:195]
	v_pk_fma_f32 v[192:193], v[234:235], v[208:209], v[192:193]
	v_pk_fma_f32 v[198:199], v[240:241], v[214:215], v[198:199]
	v_pk_fma_f32 v[196:197], v[238:239], v[212:213], v[196:197]
	v_cvt_pk_bf16_f32 v195, v194, v195
	v_cvt_pk_bf16_f32 v194, v192, v193
	v_cvt_pk_bf16_f32 v199, v198, v199
	v_cvt_pk_bf16_f32 v198, v196, v197
	s_add_u32 s24, s100, 0xb0000
	s_addc_u32 s25, s101, 0
	global_store_dwordx2 v243, v[194:195], s[24:25]
	global_store_dwordx2 v243, v[198:199], s[24:25] offset:32
	v_lshlrev_b32_e32 v184, 16, v176
	v_and_b32_e32 v185, 0xffff0000, v176
	v_lshlrev_b32_e32 v186, 16, v177
	v_and_b32_e32 v187, 0xffff0000, v177
	v_lshlrev_b32_e32 v188, 16, v178
	v_and_b32_e32 v189, 0xffff0000, v178
	v_lshlrev_b32_e32 v190, 16, v179
	v_and_b32_e32 v191, 0xffff0000, v179
	s_waitcnt lgkmcnt(2)
	v_pk_fma_f32 v[186:187], v[236:237], v[218:219], v[186:187]
	v_pk_fma_f32 v[184:185], v[234:235], v[216:217], v[184:185]
	v_pk_fma_f32 v[190:191], v[240:241], v[222:223], v[190:191]
	v_pk_fma_f32 v[188:189], v[238:239], v[220:221], v[188:189]
	v_cvt_pk_bf16_f32 v187, v186, v187
	v_cvt_pk_bf16_f32 v186, v184, v185
	v_cvt_pk_bf16_f32 v191, v190, v191
	v_cvt_pk_bf16_f32 v190, v188, v189
	s_add_u32 s24, s100, 0xe0000
	s_addc_u32 s25, s101, 0
	global_store_dwordx2 v243, v[186:187], s[24:25]
	global_store_dwordx2 v243, v[190:191], s[24:25] offset:32
	v_lshlrev_b32_e32 v192, 16, v180
	v_and_b32_e32 v193, 0xffff0000, v180
	v_lshlrev_b32_e32 v194, 16, v181
	v_and_b32_e32 v195, 0xffff0000, v181
	v_lshlrev_b32_e32 v196, 16, v182
	v_and_b32_e32 v197, 0xffff0000, v182
	v_lshlrev_b32_e32 v198, 16, v183
	v_and_b32_e32 v199, 0xffff0000, v183
	s_waitcnt lgkmcnt(0)
	v_pk_fma_f32 v[194:195], v[236:237], v[228:229], v[194:195]
	v_pk_fma_f32 v[192:193], v[234:235], v[226:227], v[192:193]
	v_pk_fma_f32 v[198:199], v[240:241], v[232:233], v[198:199]
	v_pk_fma_f32 v[196:197], v[238:239], v[230:231], v[196:197]
	v_cvt_pk_bf16_f32 v195, v194, v195
	v_cvt_pk_bf16_f32 v194, v192, v193
	v_cvt_pk_bf16_f32 v199, v198, v199
	v_cvt_pk_bf16_f32 v198, v196, v197
	s_add_u32 s24, s100, 0xf0000
	s_addc_u32 s25, s101, 0
	global_store_dwordx2 v243, v[194:195], s[24:25]
	global_store_dwordx2 v243, v[198:199], s[24:25] offset:32
	s_add_i32 s52, s52, s84
	s_cmpk_lt_i32 s52, 0x100
	s_barrier
	s_cbranch_scc0 .LBB0_1474

	.amdhsa_kernel _Z4mega6Params
		.amdhsa_group_segment_fixed_size 16
		.amdhsa_private_segment_fixed_size 0
		.amdhsa_kernarg_size 496
		.amdhsa_user_sgpr_count 2
		.amdhsa_user_sgpr_dispatch_ptr 0
		.amdhsa_user_sgpr_queue_ptr 0
		.amdhsa_user_sgpr_kernarg_segment_ptr 1
		.amdhsa_user_sgpr_dispatch_id 0
		.amdhsa_user_sgpr_kernarg_preload_length 0
		.amdhsa_user_sgpr_kernarg_preload_offset 0
		.amdhsa_user_sgpr_private_segment_size 0
		.amdhsa_uses_dynamic_stack 0
		.amdhsa_enable_private_segment 0
		.amdhsa_system_sgpr_workgroup_id_x 1
		.amdhsa_system_sgpr_workgroup_id_y 0
		.amdhsa_system_sgpr_workgroup_id_z 0
		.amdhsa_system_sgpr_workgroup_info 0
		.amdhsa_system_vgpr_workitem_id 2
		.amdhsa_next_free_vgpr 256
		.amdhsa_next_free_sgpr 102
		.amdhsa_accum_offset 256
		.amdhsa_reserve_vcc 1
		.amdhsa_float_round_mode_32 0
		.amdhsa_float_round_mode_16_64 0
		.amdhsa_float_denorm_mode_32 3
		.amdhsa_float_denorm_mode_16_64 3
		.amdhsa_dx10_clamp 1
		.amdhsa_ieee_mode 1
		.amdhsa_fp16_overflow 0
		.amdhsa_tg_split 0
		.amdhsa_exception_fp_ieee_invalid_op 0
		.amdhsa_exception_fp_denorm_src 0
		.amdhsa_exception_fp_ieee_div_zero 0
		.amdhsa_exception_fp_ieee_overflow 0
		.amdhsa_exception_fp_ieee_underflow 0
		.amdhsa_exception_fp_ieee_inexact 0
		.amdhsa_exception_int_div_zero 0
	.end_amdhsa_kernel

amdhsa.kernels:
  - .agpr_count:     0
    .args:
      - .offset:         0
        .size:           240
        .value_kind:     by_value
      - .offset:         240
        .size:           4
        .value_kind:     hidden_block_count_x
      - .offset:         244
        .size:           4
        .value_kind:     hidden_block_count_y
      - .offset:         248
        .size:           4
        .value_kind:     hidden_block_count_z
      - .offset:         252
        .size:           2
        .value_kind:     hidden_group_size_x
      - .offset:         254
        .size:           2
        .value_kind:     hidden_group_size_y
      - .offset:         256
        .size:           2
        .value_kind:     hidden_group_size_z
      - .offset:         258
        .size:           2
        .value_kind:     hidden_remainder_x
      - .offset:         260
        .size:           2
        .value_kind:     hidden_remainder_y
      - .offset:         262
        .size:           2
        .value_kind:     hidden_remainder_z
      - .offset:         280
        .size:           8
        .value_kind:     hidden_global_offset_x
      - .offset:         288
        .size:           8
        .value_kind:     hidden_global_offset_y
      - .offset:         296
        .size:           8
        .value_kind:     hidden_global_offset_z
      - .offset:         304
        .size:           2
        .value_kind:     hidden_grid_dims
      - .offset:         328
        .size:           8
        .value_kind:     hidden_multigrid_sync_arg
      - .offset:         360
        .size:           4
        .value_kind:     hidden_dynamic_lds_size
    .group_segment_fixed_size: 16
    .kernarg_segment_align: 8
    .kernarg_segment_size: 496
    .language:       OpenCL C
    .language_version:
      - 2
      - 0
    .max_flat_workgroup_size: 512
    .name:           _Z4mega6Params
    .private_segment_fixed_size: 0
    .sgpr_count:     108
    .sgpr_spill_count: 59
    .symbol:         _Z4mega6Params.kd
    .uniform_work_group_size: 1
    .uses_dynamic_stack: false
    .vgpr_count:     256
    .vgpr_spill_count: 0
    .wavefront_size: 64
